# attention B: one v_add3 per fragment address, single-copy max exchange, DMA pointers as SGPR base + 32-bit lane offset
# baseline (speedup 1.0000x reference)
.LBB0_377:
	s_cmpk_gt_i32 s33, 0x3ff
	s_cbranch_scc1 .LBB0_403
	v_lshrrev_b32_e32 v0, 2, v215
	v_lshlrev_b32_e32 v0, 5, v0
	v_or_b32_e32 v2, v181, v183
	v_and_b32_e32 v107, 64, v0
	v_bitop3_b32 v109, v0, 64, v0 bitop3:0xc
	v_lshl_add_u32 v0, v215, 2, 0
	v_lshlrev_b32_e32 v106, 7, v2
	v_add3_u32 v242, v106, v175, v176
	v_add_u32_e32 v111, 0x18000, v0
	v_lshlrev_b32_e32 v0, 4, v182
	v_lshlrev_b32_e32 v2, 2, v178
	v_sub_u32_e32 v0, v0, v2
	s_lshl_b32 s4, s92, 7
	v_subrev_u32_e32 v0, s4, v0
	v_and_b32_e32 v1, 7, v215
	v_add_u32_e32 v112, 0xfc, v0
	s_add_u32 s14, s50, 0x8221000
	v_lshlrev_b32_e32 v0, 1, v172
	s_addc_u32 s15, s51, 0
	s_lshl_b32 s16, s33, 8
	s_lshl_b32 s17, s86, 8
	v_bitop3_b32 v0, v0, v1, 4 bitop3:0x6c
	s_add_u32 s19, s50, 0x8221400
	v_mov_b32_e32 v99, 0
	v_lshlrev_b32_e32 v115, 3, v0
	v_mbcnt_lo_u32_b32 v0, -1, 0
	v_add_u32_e32 v108, 0x23f, v181
	v_sub_u32_e32 v110, 0x23f, v215
	s_mov_b32 s5, 0
	s_movk_i32 s18, 0xc00
	v_mul_u32_u24_e32 v113, 0xc00, v172
	s_addc_u32 s20, s51, 0
	s_mov_b32 s21, 0xcb8727c1
	s_movk_i32 s22, 0x284
	s_movk_i32 s23, 0xff00
	v_mov_b32_e32 v114, 0x100
	s_movk_i32 s24, 0x80f
	v_mov_b32_e32 v133, v99
	v_mov_b32_e32 v135, v99
	s_movk_i32 s25, 0xa40
	s_mov_b64 s[6:7], 0x60000
	v_lshlrev_b32_e32 v100, 1, v181
	s_add_i32 s26, 0, 0x18000
	v_mbcnt_hi_u32_b32 v116, -1, v0
	s_mov_b32 s27, s33
	s_mov_b32 s28, s33
	s_branch .LBB0_380

.LBB0_386:
	v_mov_b32_e32 v15, 0
	s_cmp_gt_i32 s35, s12
	v_mov_b32_e32 v14, v15
	v_mov_b32_e32 v13, v15
	v_mov_b32_e32 v12, v15
	v_mov_b32_e32 v11, v15
	v_mov_b32_e32 v10, v15
	v_mov_b32_e32 v9, v15
	v_mov_b32_e32 v8, v15
	v_mov_b32_e32 v7, v15
	v_mov_b32_e32 v6, v15
	v_mov_b32_e32 v5, v15
	v_mov_b32_e32 v4, v15
	v_mov_b32_e32 v3, v15
	v_mov_b32_e32 v2, v15
	v_mov_b32_e32 v1, v15
	v_mov_b32_e32 v0, v15
	v_mov_b32_e32 v31, v15
	v_mov_b32_e32 v30, v15
	v_mov_b32_e32 v29, v15
	v_mov_b32_e32 v28, v15
	v_mov_b32_e32 v27, v15
	v_mov_b32_e32 v26, v15
	v_mov_b32_e32 v25, v15
	v_mov_b32_e32 v24, v15
	v_mov_b32_e32 v23, v15
	v_mov_b32_e32 v22, v15
	v_mov_b32_e32 v21, v15
	v_mov_b32_e32 v20, v15
	v_mov_b32_e32 v19, v15
	v_mov_b32_e32 v18, v15
	v_mov_b32_e32 v17, v15
	v_mov_b32_e32 v16, v15
	v_mov_b32_e32 v101, v15
	s_cbranch_scc1 .LBB0_379
	v_or_b32_e32 v0, s37, v178
	s_add_i32 s35, s12, s41
	s_bfe_u32 s38, s16, 0x4000b
	v_sub_u32_e32 v0, v108, v0
	s_max_i32 s36, s35, 8
	s_mul_i32 s43, s38, 0xc00000
	s_and_b32 s38, s27, 7
	v_and_b32_e32 v0, 3, v0
	v_mov_b32_e32 v1, s26
	s_lshl_b32 s37, s42, 14
	s_add_i32 s36, s36, -8
	s_lshl_b32 s44, s38, 7
	v_mad_u32_u24 v117, v0, s25, v1
	s_add_i32 s37, s37, 0xfffe0000
	v_lshl_add_u32 v0, s42, 8, v112
	s_lshl_b32 s13, s13, 10
	s_add_i32 s38, s42, -5
	s_mul_i32 s45, s42, 0x60000
	v_subrev_u32_e32 v118, s13, v0
	s_mul_hi_u32 s13, s42, 0x60000
	s_add_u32 s43, s43, s45
	s_addc_u32 s13, 0, s13
	s_or_b32 s43, s43, s44
	s_mulk_i32 s39, 0x6000
	v_add_u32_e32 v0, s39, v113
	s_add_u32 s44, s14, s43
	v_add_u32_e32 v98, v0, v32
	s_addc_u32 s45, s15, s13
	s_mov_b64 s[98:99], s[44:45]
	v_lshlrev_b32_e32 v102, 1, v98
	s_add_u32 s44, s19, s43
	v_add_u32_e32 v98, v0, v115
	s_addc_u32 s45, s20, s13
	s_sub_i32 s39, 0, s12
	s_sub_i32 s12, s12, s42
	v_mov_b32_e32 v101, 0
	s_mov_b64 s[100:101], s[44:45]
	v_lshlrev_b32_e32 v104, 1, v98
	s_add_i32 s42, s12, 11
	v_mov_b32_e32 v119, 0xf149f2ca
	v_mov_b32_e32 v136, 0
	v_mov_b32_e32 v137, 0
	v_mov_b32_e32 v138, 0
	v_mov_b32_e32 v139, 0
	v_mov_b32_e32 v140, 0
	v_mov_b32_e32 v141, 0
	v_mov_b32_e32 v142, 0
	v_mov_b32_e32 v143, 0
	v_mov_b32_e32 v144, 0
	v_mov_b32_e32 v145, 0
	v_mov_b32_e32 v146, 0
	v_mov_b32_e32 v147, 0
	v_mov_b32_e32 v148, 0
	v_mov_b32_e32 v149, 0
	v_mov_b32_e32 v150, 0
	v_mov_b32_e32 v151, 0
	v_mov_b32_e32 v164, 0
	v_mov_b32_e32 v165, 0xf149f2ca
	v_mov_b32_e32 v16, 0
	v_mov_b32_e32 v17, v101
	v_mov_b32_e32 v18, v101
	v_mov_b32_e32 v19, v101
	v_mov_b32_e32 v20, v101
	v_mov_b32_e32 v21, v101
	v_mov_b32_e32 v22, v101
	v_mov_b32_e32 v23, v101
	v_mov_b32_e32 v24, v101
	v_mov_b32_e32 v25, v101
	v_mov_b32_e32 v26, v101
	v_mov_b32_e32 v27, v101
	v_mov_b32_e32 v28, v101
	v_mov_b32_e32 v29, v101
	v_mov_b32_e32 v30, v101
	v_mov_b32_e32 v31, v101
	v_mov_b32_e32 v0, v101
	v_mov_b32_e32 v1, v101
	v_mov_b32_e32 v2, v101
	v_mov_b32_e32 v3, v101
	v_mov_b32_e32 v4, v101
	v_mov_b32_e32 v5, v101
	v_mov_b32_e32 v6, v101
	v_mov_b32_e32 v7, v101
	v_mov_b32_e32 v8, v101
	v_mov_b32_e32 v9, v101
	v_mov_b32_e32 v10, v101
	v_mov_b32_e32 v11, v101
	v_mov_b32_e32 v12, v101
	v_mov_b32_e32 v13, v101
	v_mov_b32_e32 v14, v101
	v_mov_b32_e32 v15, v101
	s_cmp_lt_i32 s42, 2
	s_mov_b64 s[12:13], -1
	s_cbranch_scc0 .LBB0_393

.LBB0_395:
	s_waitcnt lgkmcnt(0)
	s_barrier
	s_cmp_ge_i32 s38, s31
	s_cbranch_scc1 .LBB0_397
	s_add_i32 s12, s37, 0xc000
	s_and_b32 s12, s12, 0xc000
	s_add_i32 s12, s34, s12
	s_mov_b32 m0, s12
	s_nop 0
	global_load_lds_dwordx4 v102, s[98:99]
	s_add_i32 m0, s12, 0x2000
	s_nop 0
	global_load_lds_dwordx4 v104, s[100:101]
.LBB0_397:
	s_add_i32 s43, s38, -3
	s_cmp_lt_u32 s43, s36
	s_cselect_b64 s[12:13], -1, 0
	s_cmp_gt_i32 s43, s35
	s_cselect_b64 s[44:45], -1, 0
	s_or_b64 s[12:13], s[12:13], s[44:45]
	s_and_b64 vcc, exec, s[12:13]
	s_cbranch_vccnz .LBB0_401
	s_and_b32 s12, s37, 0xc000
	s_add_i32 s12, s12, 0
	v_add3_u32 v126, s12, v174, v173
	v_add3_u32 v127, s12, v174, v177
	v_add3_u32 v128, s12, v174, v179
	v_add3_u32 v129, s12, v174, v180
	ds_read_b128 v[152:155], v126
	ds_read_b128 v[156:159], v126 offset:4096
	ds_read_b128 v[160:163], v127
	ds_read_b128 v[184:187], v127 offset:4096
	ds_read_b128 v[188:191], v128
	ds_read_b128 v[192:195], v128 offset:4096
	ds_read_b128 v[244:247], v129
	ds_read_b128 v[248:251], v129 offset:4096
	v_and_b32_e32 v131, -16, v118
	v_add_u32_e32 v131, v117, v131
	s_waitcnt lgkmcnt(6)
	v_mfma_f32_32x32x16_bf16 v[32:47], v[152:155], v[64:67], v[136:151]
	v_mfma_f32_32x32x16_bf16 v[48:63], v[156:159], v[64:67], v[136:151]
	ds_read_b128 v[200:203], v131
	ds_read_b128 v[204:207], v131 offset:32
	ds_read_b128 v[208:211], v131 offset:64
	ds_read_b128 v[252:255], v131 offset:96
	s_waitcnt lgkmcnt(8)
	v_mfma_f32_32x32x16_bf16 v[32:47], v[160:163], v[68:71], v[32:47]
	v_mfma_f32_32x32x16_bf16 v[48:63], v[184:187], v[68:71], v[48:63]
	s_waitcnt lgkmcnt(6)
	v_mfma_f32_32x32x16_bf16 v[32:47], v[188:191], v[72:75], v[32:47]
	v_mfma_f32_32x32x16_bf16 v[48:63], v[192:195], v[72:75], v[48:63]
	s_waitcnt lgkmcnt(4)
	v_mfma_f32_32x32x16_bf16 v[32:47], v[244:247], v[76:79], v[32:47]
	v_mfma_f32_32x32x16_bf16 v[48:63], v[248:251], v[76:79], v[48:63]
	v_add3_u32 v130, s12, v242, v109
	v_add3_u32 v129, s12, v242, v107
	s_waitcnt lgkmcnt(0)
	ds_read_b64_tr_b16 v[152:153], v129 offset:8192
	ds_read_b64_tr_b16 v[154:155], v129 offset:9216
	ds_read_b64_tr_b16 v[156:157], v130 offset:8192
	ds_read_b64_tr_b16 v[158:159], v130 offset:9216
	ds_read_b64_tr_b16 v[160:161], v129 offset:10240
	ds_read_b64_tr_b16 v[162:163], v129 offset:11264
	ds_read_b64_tr_b16 v[184:185], v130 offset:10240
	ds_read_b64_tr_b16 v[186:187], v130 offset:11264
	ds_read_b64_tr_b16 v[188:189], v129 offset:12288
	ds_read_b64_tr_b16 v[190:191], v129 offset:13312
	ds_read_b64_tr_b16 v[192:193], v130 offset:12288
	v_fmamk_f32 v32, v32, 0x3e38aa3b, v200
	v_fmamk_f32 v33, v33, 0x3e38aa3b, v201
	v_fmamk_f32 v34, v34, 0x3e38aa3b, v202
	v_fmamk_f32 v35, v35, 0x3e38aa3b, v203
	v_fmamk_f32 v36, v36, 0x3e38aa3b, v204
	v_fmamk_f32 v37, v37, 0x3e38aa3b, v205
	v_fmamk_f32 v38, v38, 0x3e38aa3b, v206
	v_fmamk_f32 v39, v39, 0x3e38aa3b, v207
	v_fmamk_f32 v40, v40, 0x3e38aa3b, v208
	v_fmamk_f32 v41, v41, 0x3e38aa3b, v209
	v_fmamk_f32 v42, v42, 0x3e38aa3b, v210
	v_fmamk_f32 v43, v43, 0x3e38aa3b, v211
	v_fmamk_f32 v44, v44, 0x3e38aa3b, v252
	v_fmamk_f32 v45, v45, 0x3e38aa3b, v253
	v_fmamk_f32 v46, v46, 0x3e38aa3b, v254
	v_fmamk_f32 v47, v47, 0x3e38aa3b, v255
	ds_read_b128 v[200:203], v131 offset:128
	ds_read_b128 v[204:207], v131 offset:160
	ds_read_b128 v[208:211], v131 offset:192
	ds_read_b128 v[252:255], v131 offset:224
	s_waitcnt lgkmcnt(0)
	ds_read_b64_tr_b16 v[194:195], v130 offset:13312
	ds_read_b64_tr_b16 v[244:245], v129 offset:14336
	ds_read_b64_tr_b16 v[246:247], v129 offset:15360
	ds_read_b64_tr_b16 v[248:249], v130 offset:14336
	v_fmamk_f32 v48, v48, 0x3e38aa3b, v200
	v_fmamk_f32 v49, v49, 0x3e38aa3b, v201
	v_fmamk_f32 v50, v50, 0x3e38aa3b, v202
	v_fmamk_f32 v51, v51, 0x3e38aa3b, v203
	v_fmamk_f32 v52, v52, 0x3e38aa3b, v204
	v_fmamk_f32 v53, v53, 0x3e38aa3b, v205
	v_fmamk_f32 v54, v54, 0x3e38aa3b, v206
	v_fmamk_f32 v55, v55, 0x3e38aa3b, v207
	v_fmamk_f32 v56, v56, 0x3e38aa3b, v208
	v_fmamk_f32 v57, v57, 0x3e38aa3b, v209
	v_fmamk_f32 v58, v58, 0x3e38aa3b, v210
	v_fmamk_f32 v59, v59, 0x3e38aa3b, v211
	v_fmamk_f32 v60, v60, 0x3e38aa3b, v252
	v_fmamk_f32 v61, v61, 0x3e38aa3b, v253
	v_fmamk_f32 v62, v62, 0x3e38aa3b, v254
	v_fmamk_f32 v63, v63, 0x3e38aa3b, v255
	v_max3_f32 v125, v32, v33, v34
	v_max3_f32 v126, v35, v36, v37
	v_max3_f32 v127, v38, v39, v40
	v_max3_f32 v128, v41, v42, v43
	v_max3_f32 v125, v125, v44, v45
	v_max3_f32 v126, v126, v46, v47
	v_max3_f32 v127, v127, v48, v49
	v_max3_f32 v128, v128, v50, v51
	v_max3_f32 v125, v125, v52, v53
	v_max3_f32 v126, v126, v54, v55
	v_max3_f32 v127, v127, v56, v57
	v_max3_f32 v128, v128, v58, v59
	v_max3_f32 v125, v125, v60, v61
	v_max3_f32 v126, v126, v62, v63
	v_max3_f32 v125, v125, v126, v127
	v_max_f32_e32 v125, v125, v128
	v_mov_b32_e32 v126, v125
	s_nop 1
	v_permlane32_swap_b32_e32 v125, v126
	v_max_f32_e32 v125, v125, v126
	v_add_f32_e32 v126, 0x41000000, v165
	v_cmp_gt_f32_e32 vcc, v125, v126
	s_cbranch_vccz .Lb_pv
	v_add_f32_e32 v125, v125, v164
	v_max_f32_e32 v127, v119, v125
	v_sub_f32_e32 v126, v119, v127
	v_exp_f32_e32 v126, v126
	v_sub_f32_e32 v128, v164, v127
	v_mov_b32_e32 v119, v127
	v_add_f32_e32 v32, v32, v128
	v_add_f32_e32 v33, v33, v128
	v_add_f32_e32 v34, v34, v128
	v_add_f32_e32 v35, v35, v128
	v_add_f32_e32 v36, v36, v128
	v_add_f32_e32 v37, v37, v128
	v_add_f32_e32 v38, v38, v128
	v_add_f32_e32 v39, v39, v128
	v_add_f32_e32 v40, v40, v128
	v_add_f32_e32 v41, v41, v128
	v_add_f32_e32 v42, v42, v128
	v_add_f32_e32 v43, v43, v128
	v_add_f32_e32 v44, v44, v128
	v_add_f32_e32 v45, v45, v128
	v_add_f32_e32 v46, v46, v128
	v_add_f32_e32 v47, v47, v128
	v_add_f32_e32 v48, v48, v128
	v_add_f32_e32 v49, v49, v128
	v_add_f32_e32 v50, v50, v128
	v_add_f32_e32 v51, v51, v128
	v_add_f32_e32 v52, v52, v128
	v_add_f32_e32 v53, v53, v128
	v_add_f32_e32 v54, v54, v128
	v_add_f32_e32 v55, v55, v128
	v_add_f32_e32 v56, v56, v128
	v_add_f32_e32 v57, v57, v128
	v_add_f32_e32 v58, v58, v128
	v_add_f32_e32 v59, v59, v128
	v_add_f32_e32 v60, v60, v128
	v_add_f32_e32 v61, v61, v128
	v_add_f32_e32 v62, v62, v128
	v_add_f32_e32 v63, v63, v128
	v_pk_mul_f32 v[0:1], v[0:1], v[126:127] op_sel_hi:[1,0]
	v_pk_mul_f32 v[2:3], v[2:3], v[126:127] op_sel_hi:[1,0]
	v_pk_mul_f32 v[4:5], v[4:5], v[126:127] op_sel_hi:[1,0]
	v_pk_mul_f32 v[6:7], v[6:7], v[126:127] op_sel_hi:[1,0]
	v_pk_mul_f32 v[8:9], v[8:9], v[126:127] op_sel_hi:[1,0]
	v_pk_mul_f32 v[10:11], v[10:11], v[126:127] op_sel_hi:[1,0]
	v_pk_mul_f32 v[12:13], v[12:13], v[126:127] op_sel_hi:[1,0]
	v_pk_mul_f32 v[14:15], v[14:15], v[126:127] op_sel_hi:[1,0]
	v_pk_mul_f32 v[16:17], v[16:17], v[126:127] op_sel_hi:[1,0]
	v_pk_mul_f32 v[18:19], v[18:19], v[126:127] op_sel_hi:[1,0]
	v_pk_mul_f32 v[20:21], v[20:21], v[126:127] op_sel_hi:[1,0]
	v_pk_mul_f32 v[22:23], v[22:23], v[126:127] op_sel_hi:[1,0]
	v_pk_mul_f32 v[24:25], v[24:25], v[126:127] op_sel_hi:[1,0]
	v_pk_mul_f32 v[26:27], v[26:27], v[126:127] op_sel_hi:[1,0]
	v_pk_mul_f32 v[28:29], v[28:29], v[126:127] op_sel_hi:[1,0]
	v_pk_mul_f32 v[30:31], v[30:31], v[126:127] op_sel_hi:[1,0]
	v_mul_f32_e32 v101, v101, v126
	v_mul_f32_e32 v128, 0xc0b17218, v127
	v_mov_b32_e32 v136, v128
	v_mov_b32_e32 v137, v128
	v_mov_b32_e32 v138, v128
	v_mov_b32_e32 v139, v128
	v_mov_b32_e32 v140, v128
	v_mov_b32_e32 v141, v128
	v_mov_b32_e32 v142, v128
	v_mov_b32_e32 v143, v128
	v_mov_b32_e32 v144, v128
	v_mov_b32_e32 v145, v128
	v_mov_b32_e32 v146, v128
	v_mov_b32_e32 v147, v128
	v_mov_b32_e32 v148, v128
	v_mov_b32_e32 v149, v128
	v_mov_b32_e32 v150, v128
	v_mov_b32_e32 v151, v128
	v_mov_b32_e32 v164, v127
	v_mov_b32_e32 v165, 0

.LBB0_401:
	s_addk_i32 s37, 0x4000
	s_add_i32 s12, s38, 1
	s_add_i32 s13, s38, -2
	s_add_i32 s42, s42, -1
	v_add_u32_e32 v118, 0x100, v118
	s_add_u32 s98, s98, s6
	s_addc_u32 s99, s99, s7
	s_add_u32 s100, s100, s6
	s_addc_u32 s101, s101, s7
	s_cmp_lt_i32 s13, s31
	s_cbranch_scc0 .LBB0_379
	s_mov_b32 s38, s12
	s_cmp_lt_i32 s42, 2
	s_mov_b64 s[12:13], -1
	s_cbranch_scc1 .LBB0_388
	s_branch .LBB0_393
